# prefetch loads land in a dedicated register; all unit-tail store drains removed; tail split robust for any grid
# speedup vs baseline: 1.0046x; 1.0046x over previous
.LBB0_232:
	s_mov_b64 s[4:5], 0
	v_readlane_b32 s83, v254, 10
	v_readlane_b32 s84, v254, 11
	v_readlane_b32 s85, v254, 12
	s_barrier

.LBB0_246:
	s_cmp_lt_i32 s11, 0
	s_mov_b32 s83, 0
	s_barrier
	s_cbranch_scc1 .LBB0_248
	v_lshl_or_b32 v132, s11, 8, v226
	v_lshlrev_b64 v[142:143], 11, v[132:133]
	v_add_u32_e32 v144, s10, v226
	v_lshl_add_u64 v[142:143], v[158:159], 0, v[142:143]
	v_ashrrev_i32_e32 v145, 31, v144
	v_lshlrev_b64 v[144:145], 11, v[144:145]
	global_load_dword v255, v[142:143], off
	v_lshl_add_u64 v[144:145], v[134:135], 0, v[144:145]
	global_load_dword v255, v[144:145], off
	s_branch .LBB0_249

.LBB0_759:
	s_cmp_lt_i32 s23, 0
	s_mov_b32 s31, 0
	s_barrier
	s_cbranch_scc1 .LBB0_761
	v_lshl_or_b32 v134, s23, 8, v226
	v_mad_u64_u32 v[142:143], s[6:7], v134, s26, v[158:159]
	v_add_u32_e32 v134, s22, v226
	global_load_dword v255, v[142:143], off
	v_mad_i64_i32 v[144:145], s[6:7], v134, s26, v[136:137]
	global_load_dword v255, v[144:145], off
	s_branch .LBB0_762

.LBB0_917:
	s_cmp_lt_i32 s37, 0
	s_barrier
	s_cbranch_scc1 .LBB0_919
	v_lshl_or_b32 v134, s37, 8, v226
	v_lshlrev_b64 v[144:145], 11, v[134:135]
	v_add_u32_e32 v146, s36, v226
	v_lshl_add_u64 v[144:145], v[158:159], 0, v[144:145]
	v_ashrrev_i32_e32 v147, 31, v146
	v_lshlrev_b64 v[146:147], 11, v[146:147]
	global_load_dword v255, v[144:145], off
	v_lshl_add_u64 v[146:147], v[136:137], 0, v[146:147]
	global_load_dword v255, v[146:147], off
	s_branch .LBB0_920

.LBB0_956:
	s_mul_hi_u32 s0, s67, 0x580
	s_mul_i32 s0, s0, s66
	s_sub_i32 s0, 0x580, s0
	s_sub_i32 s1, s0, s66
	s_cmp_ge_u32 s0, s66
	s_cselect_b32 s0, s1, s0
	s_sub_i32 s1, s0, s66
	s_cmp_ge_u32 s0, s66
	s_cselect_b32 s3, s1, s0
	s_cmp_lt_i32 s83, s3
	s_cbranch_scc1 .Ltail1_unitwg
	s_sub_i32 s2, s83, s3
	s_movk_i32 s98, 0x4d0
	s_cmp_eq_u32 s3, 0
	s_cselect_b32 s98, 0x6d0, s98
	s_sub_i32 s99, s84, s3
	s_branch .Ltail1_common

.LBB0_1131:
	s_cmp_lt_i32 s25, 0
	s_mov_b32 s6, 0
	s_barrier
	s_cbranch_scc1 .LBB0_1133
	v_lshl_or_b32 v138, s25, 8, v226
	v_mad_u64_u32 v[146:147], s[26:27], v138, s47, v[134:135]
	v_add_u32_e32 v138, s24, v226
	global_load_dword v255, v[146:147], off
	v_mad_i64_i32 v[148:149], s[24:25], v138, s47, v[140:141]
	global_load_dword v255, v[148:149], off
	s_branch .LBB0_1134

.LBB0_1259:
	s_or_b64 exec, exec, s[0:1]
	v_readlane_b32 s2, v254, 0
	v_readlane_b32 s3, v254, 1
	s_waitcnt lgkmcnt(0)
	s_barrier
	s_load_dwordx4 s[8:11], s[2:3], 0xe8
	s_mov_b64 s[0:1], 0xe80000
	v_lshl_add_u64 v[136:137], v[154:155], 0, s[0:1]
	v_mov_b32_e32 v139, 0
	v_mov_b32_e32 v131, v139
	s_waitcnt lgkmcnt(0)
	s_add_u32 s2, s10, 0xb280000
	s_addc_u32 s3, s11, 0
	s_add_u32 s0, s8, 0x7800000
	s_addc_u32 s1, s9, 0
	s_add_u32 s4, s8, 0x5800000
	s_mov_b64 s[6:7], 0xe80100
	v_lshl_add_u64 v[140:141], v[136:137], 0, v[130:131]
	s_addc_u32 s5, s9, 0
	v_lshl_add_u64 v[142:143], v[154:155], 0, s[6:7]
	s_mov_b32 s9, 0
	v_mov_b64_e32 v[144:145], 0x300
	v_mov_b64_e32 v[146:147], 0x2ff
	s_movk_i32 s28, 0x61
	s_mov_b64 s[12:13], 0x40000
	s_mov_b64 s[14:15], 0x80
	s_mov_b64 s[16:17], 0x40080
	s_mov_b64 s[18:19], 0x4280100
	s_movk_i32 s29, 0x108
	s_movk_i32 s30, 0x1080
	s_movk_i32 s31, 0x210
	s_mov_b32 s33, 0x7280000
	v_mov_b32_e32 v1, 1
	s_mov_b32 s34, 0
	s_waitcnt vmcnt(0)
	s_branch .LBB0_1262
.LBB0_1260:
	s_mov_b64 s[6:7], 0
	s_barrier

.LBB0_1274:
	s_cmp_lt_i32 s26, 0
	s_mov_b32 s20, 0
	s_barrier
	s_cbranch_scc1 .LBB0_1276
	v_lshl_or_b32 v138, s26, 8, v226
	v_lshlrev_b64 v[148:149], 11, v[138:139]
	v_add_u32_e32 v150, s8, v226
	v_lshl_add_u64 v[148:149], v[158:159], 0, v[148:149]
	v_ashrrev_i32_e32 v151, 31, v150
	v_lshlrev_b64 v[150:151], 11, v[150:151]
	global_load_dword v255, v[148:149], off
	v_lshl_add_u64 v[150:151], v[140:141], 0, v[150:151]
	global_load_dword v255, v[150:151], off
	s_branch .LBB0_1277

.LBB0_1648:
	s_cmp_lt_i32 s21, 0
	s_mov_b32 s6, 0
	s_barrier
	s_cbranch_scc1 .LBB0_1650
	v_lshl_or_b32 v138, s21, 8, v226
	v_lshlrev_b64 v[146:147], 11, v[138:139]
	v_add_u32_e32 v148, s20, v226
	v_lshl_add_u64 v[146:147], v[158:159], 0, v[146:147]
	v_ashrrev_i32_e32 v149, 31, v148
	v_lshlrev_b64 v[148:149], 11, v[148:149]
	global_load_dword v255, v[146:147], off
	v_lshl_add_u64 v[148:149], v[140:141], 0, v[148:149]
	global_load_dword v255, v[148:149], off
	s_branch .LBB0_1651

.LBB0_1791:
	s_cmp_lt_i32 s37, 0
	s_barrier
	s_cbranch_scc1 .LBB0_1793
	v_lshl_or_b32 v138, s37, 8, v226
	v_lshlrev_b64 v[148:149], 11, v[138:139]
	v_add_u32_e32 v150, s36, v226
	v_lshl_add_u64 v[148:149], v[158:159], 0, v[148:149]
	v_ashrrev_i32_e32 v151, 31, v150
	v_lshlrev_b64 v[150:151], 11, v[150:151]
	global_load_dword v255, v[148:149], off
	v_lshl_add_u64 v[150:151], v[140:141], 0, v[150:151]
	global_load_dword v255, v[150:151], off
	s_branch .LBB0_1794

.LBB0_1917:
	s_cmp_lt_i32 s25, 0
	s_mov_b32 s4, 0
	s_barrier
	s_cbranch_scc1 .LBB0_1919
	v_lshl_or_b32 v130, s25, 8, v226
	v_mad_u64_u32 v[144:145], s[26:27], v130, s47, v[134:135]
	v_add_u32_e32 v130, s24, v226
	global_load_dword v255, v[144:145], off
	v_mad_i64_i32 v[146:147], s[24:25], v130, s47, v[138:139]
	global_load_dword v255, v[146:147], off
	s_branch .LBB0_1920

	.amdhsa_kernel _Z11mega_kernel6Params
		.amdhsa_group_segment_fixed_size 0
		.amdhsa_private_segment_fixed_size 0
		.amdhsa_kernarg_size 504
		.amdhsa_user_sgpr_count 2
		.amdhsa_user_sgpr_dispatch_ptr 0
		.amdhsa_user_sgpr_queue_ptr 0
		.amdhsa_user_sgpr_kernarg_segment_ptr 1
		.amdhsa_user_sgpr_dispatch_id 0
		.amdhsa_user_sgpr_kernarg_preload_length 0
		.amdhsa_user_sgpr_kernarg_preload_offset 0
		.amdhsa_user_sgpr_private_segment_size 0
		.amdhsa_uses_dynamic_stack 0
		.amdhsa_enable_private_segment 0
		.amdhsa_system_sgpr_workgroup_id_x 1
		.amdhsa_system_sgpr_workgroup_id_y 0
		.amdhsa_system_sgpr_workgroup_id_z 0
		.amdhsa_system_sgpr_workgroup_info 0
		.amdhsa_system_vgpr_workitem_id 0
		.amdhsa_next_free_vgpr 256
		.amdhsa_next_free_sgpr 102
		.amdhsa_accum_offset 256
		.amdhsa_reserve_vcc 1
		.amdhsa_float_round_mode_32 0
		.amdhsa_float_round_mode_16_64 0
		.amdhsa_float_denorm_mode_32 3
		.amdhsa_float_denorm_mode_16_64 3
		.amdhsa_dx10_clamp 1
		.amdhsa_ieee_mode 1
		.amdhsa_fp16_overflow 0
		.amdhsa_tg_split 0
		.amdhsa_exception_fp_ieee_invalid_op 0
		.amdhsa_exception_fp_denorm_src 0
		.amdhsa_exception_fp_ieee_div_zero 0
		.amdhsa_exception_fp_ieee_overflow 0
		.amdhsa_exception_fp_ieee_underflow 0
		.amdhsa_exception_fp_ieee_inexact 0
		.amdhsa_exception_int_div_zero 0
	.end_amdhsa_kernel

amdhsa.kernels:
  - .agpr_count:     0
    .args:
      - .offset:         0
        .size:           248
        .value_kind:     by_value
      - .offset:         248
        .size:           4
        .value_kind:     hidden_block_count_x
      - .offset:         252
        .size:           4
        .value_kind:     hidden_block_count_y
      - .offset:         256
        .size:           4
        .value_kind:     hidden_block_count_z
      - .offset:         260
        .size:           2
        .value_kind:     hidden_group_size_x
      - .offset:         262
        .size:           2
        .value_kind:     hidden_group_size_y
      - .offset:         264
        .size:           2
        .value_kind:     hidden_group_size_z
      - .offset:         266
        .size:           2
        .value_kind:     hidden_remainder_x
      - .offset:         268
        .size:           2
        .value_kind:     hidden_remainder_y
      - .offset:         270
        .size:           2
        .value_kind:     hidden_remainder_z
      - .offset:         288
        .size:           8
        .value_kind:     hidden_global_offset_x
      - .offset:         296
        .size:           8
        .value_kind:     hidden_global_offset_y
      - .offset:         304
        .size:           8
        .value_kind:     hidden_global_offset_z
      - .offset:         312
        .size:           2
        .value_kind:     hidden_grid_dims
      - .offset:         368
        .size:           4
        .value_kind:     hidden_dynamic_lds_size
    .group_segment_fixed_size: 0
    .kernarg_segment_align: 8
    .kernarg_segment_size: 504
    .language:       OpenCL C
    .language_version:
      - 2
      - 0
    .max_flat_workgroup_size: 512
    .name:           _Z11mega_kernel6Params
    .private_segment_fixed_size: 0
    .sgpr_count:     108
    .sgpr_spill_count: 54
    .symbol:         _Z11mega_kernel6Params.kd
    .uniform_work_group_size: 1
    .uses_dynamic_stack: false
    .vgpr_count:     256
    .vgpr_spill_count: 0
    .wavefront_size: 64
